# attention tile steps (NA, MEM, dilated A+B): hoisted fragment addresses, batched bias reads, early V reads, permlane32 max, interleaved rescale
# speedup vs baseline: 1.0187x; 1.0187x over previous
.LBB0_356:
	v_and_b32_e32 v14, 31, v169
	v_lshrrev_b32_e32 v15, 5, v169
	v_lshlrev_b32_e32 v2, 2, v169
	v_and_b32_e32 v2, 12, v2
	v_bfe_u32 v3, v169, 2, 2
	v_or_b32_e32 v2, v2, v3
	v_xor_b32_e32 v250, v15, v2
	v_lshlrev_b32_e32 v250, 4, v250
	v_lshl_add_u32 v248, v14, 8, v250
	v_lshl_or_b32 v14, v15, 2, v3
	v_lshlrev_b32_e32 v2, 2, v3
	v_or_b32_e32 v2, v2, v15
	v_bfe_u32 v250, v169, 1, 1
	v_lshrrev_b32_e32 v251, 3, v169
	v_and_or_b32 v250, v251, 2, v250
	v_xor_b32_e32 v250, v250, v2
	v_lshlrev_b32_e32 v250, 4, v250
	v_lshl_add_u32 v250, v14, 8, v250
	v_lshlrev_b32_e32 v251, 3, v169
	v_and_b32_e32 v251, 8, v251
	v_add_u32_e32 v249, v250, v251
	v_add_u32_e32 v249, 0x2000, v249
	v_mov_b32_e32 v14, v1
	v_mov_b32_e32 v15, v1
	v_mov_b32_e32 v0, v1
	v_mov_b32_e32 v2, v1
	v_mov_b32_e32 v3, v1
	v_mov_b32_e32 v4, v1
	v_mov_b32_e32 v5, v1
	v_mov_b32_e32 v6, v1
	v_mov_b32_e32 v7, v1
	v_mov_b32_e32 v8, v1
	v_mov_b32_e32 v9, v1
	v_mov_b32_e32 v10, v1
	v_mov_b32_e32 v11, v1
	v_mov_b32_e32 v12, v1
	v_mov_b32_e32 v13, v1
	v_mov_b64_e32 v[64:65], v[14:15]
	v_mov_b64_e32 v[48:49], v[14:15]
	v_mov_b64_e32 v[32:33], v[14:15]
	s_waitcnt vmcnt(0) lgkmcnt(0)
	v_mov_b64_e32 v[82:83], v[124:125]
	v_mov_b64_e32 v[86:87], v[120:121]
	v_mov_b64_e32 v[90:91], v[116:117]
	v_mov_b64_e32 v[130:131], v[114:115]
	v_mov_b64_e32 v[134:135], v[110:111]
	v_mov_b64_e32 v[138:139], v[106:107]
	v_mov_b64_e32 v[142:143], v[102:103]
	v_mov_b64_e32 v[146:147], v[98:99]
	s_bitcmp1_b32 s56, 0
	v_mov_b64_e32 v[62:63], v[12:13]
	v_mov_b64_e32 v[60:61], v[10:11]
	v_mov_b64_e32 v[58:59], v[8:9]
	v_mov_b64_e32 v[56:57], v[6:7]
	v_mov_b64_e32 v[54:55], v[4:5]
	v_mov_b64_e32 v[52:53], v[2:3]
	v_mov_b64_e32 v[50:51], v[0:1]
	v_mov_b64_e32 v[46:47], v[12:13]
	v_mov_b64_e32 v[44:45], v[10:11]
	v_mov_b64_e32 v[42:43], v[8:9]
	v_mov_b64_e32 v[40:41], v[6:7]
	v_mov_b64_e32 v[38:39], v[4:5]
	v_mov_b64_e32 v[36:37], v[2:3]
	v_mov_b64_e32 v[34:35], v[0:1]
	v_mov_b64_e32 v[30:31], v[12:13]
	v_mov_b64_e32 v[28:29], v[10:11]
	v_mov_b64_e32 v[26:27], v[8:9]
	v_mov_b64_e32 v[24:25], v[6:7]
	v_mov_b64_e32 v[22:23], v[4:5]
	v_mov_b64_e32 v[20:21], v[2:3]
	v_mov_b64_e32 v[18:19], v[0:1]
	v_mov_b64_e32 v[16:17], v[14:15]
	v_mov_b64_e32 v[84:85], v[126:127]
	v_mov_b64_e32 v[88:89], v[122:123]
	v_mov_b64_e32 v[92:93], v[118:119]
	v_mov_b64_e32 v[128:129], v[112:113]
	v_mov_b64_e32 v[132:133], v[108:109]
	v_mov_b64_e32 v[136:137], v[104:105]
	v_mov_b64_e32 v[140:141], v[100:101]
	v_mov_b64_e32 v[144:145], v[96:97]
	s_cselect_b64 s[80:81], -1, 0
	s_mov_b32 s77, 0
	v_mov_b32_e32 v199, 0xc61c4000
	v_mov_b32_e32 v198, 0
	s_mov_b64 s[26:27], s[4:5]
	s_mov_b64 s[12:13], s[86:87]
	v_mov_b32_e32 v94, v182
	v_mov_b32_e32 v183, v171
	s_mov_b32 s98, s61
	s_mov_b32 s50, s68
	s_mov_b32 s67, s51
	s_mov_b32 s69, s52
	s_mov_b32 s65, s57
	s_mov_b32 s53, s70
	s_mov_b32 s71, s60
	s_mov_b32 s19, s54
	s_mov_b32 s63, s55
	s_mov_b32 s59, s64
	v_mov_b64_e32 v[14:15], v[12:13]
	v_mov_b64_e32 v[12:13], v[10:11]
	v_mov_b64_e32 v[10:11], v[8:9]
	v_mov_b64_e32 v[8:9], v[6:7]
	v_mov_b64_e32 v[6:7], v[4:5]
	v_mov_b64_e32 v[4:5], v[2:3]
	v_mov_b64_e32 v[2:3], v[0:1]
	s_branch .LBB0_358

.LBB0_398:
	s_andn2_b64 vcc, exec, s[0:1]
	s_cbranch_vccnz .LBB0_408
	s_lshl_b32 s0, s59, 14
	s_add_i32 s28, s0, 0x2000
	v_add_u32_e32 v250, s0, v248
	v_add_u32_e32 v251, s0, v249
	v_xor_b32_e32 v0, 32, v250
	v_xor_b32_e32 v95, 64, v250
	ds_read_b128 v[66:69], v250
	ds_read_b128 v[216:219], v0
	v_xor_b32_e32 v0, 0x60, v250
	ds_read_b128 v[220:223], v95
	v_xor_b32_e32 v95, 0x80, v250
	ds_read_b128 v[224:227], v0
	v_xor_b32_e32 v0, 0xa0, v250
	ds_read_b128 v[228:231], v95
	v_xor_b32_e32 v95, 0xc0, v250
	ds_read_b128 v[232:235], v0
	v_xor_b32_e32 v0, 0xe0, v250
	ds_read_b128 v[236:239], v95
	ds_read_b128 v[240:243], v0
	s_waitcnt lgkmcnt(7)
	v_mfma_f32_32x32x16_bf16 v[66:81], v[66:69], v[82:85], 0
	s_and_b32 s0, s77, 3
	s_sub_i32 s16, s0, s84
	v_readlane_b32 s0, v254, 31
	s_add_i32 s17, s0, s77
	s_and_b64 s[0:1], s[10:11], exec
	s_cselect_b32 s29, s16, s17
	s_cmp_lt_i32 s29, 2
	s_waitcnt lgkmcnt(6)
	v_mfma_f32_32x32x16_bf16 v[66:81], v[216:219], v[86:89], v[66:81]
	s_waitcnt lgkmcnt(5)
	v_mfma_f32_32x32x16_bf16 v[66:81], v[220:223], v[90:93], v[66:81]
	s_waitcnt lgkmcnt(4)
	v_mfma_f32_32x32x16_bf16 v[66:81], v[224:227], v[128:131], v[66:81]
	s_waitcnt lgkmcnt(3)
	v_mfma_f32_32x32x16_bf16 v[66:81], v[228:231], v[132:135], v[66:81]
	s_waitcnt lgkmcnt(2)
	v_mfma_f32_32x32x16_bf16 v[66:81], v[232:235], v[136:139], v[66:81]
	s_waitcnt lgkmcnt(1)
	v_mfma_f32_32x32x16_bf16 v[66:81], v[236:239], v[140:143], v[66:81]
	s_waitcnt lgkmcnt(0)
	v_mfma_f32_32x32x16_bf16 v[66:81], v[240:243], v[144:147], v[66:81]
	v_xor_b32_e32 v0, 0x820, v251
	v_xor_b32_e32 v95, 64, v251
	v_xor_b32_e32 v250, 0x860, v251
	v_xor_b32_e32 v244, 0x80, v251
	v_xor_b32_e32 v245, 0x8a0, v251
	v_xor_b32_e32 v246, 0xc0, v251
	v_xor_b32_e32 v247, 0x8e0, v251
	ds_read_b64_tr_b16 v[216:217], v251
	ds_read_b64_tr_b16 v[218:219], v0
	ds_read_b64_tr_b16 v[220:221], v95
	ds_read_b64_tr_b16 v[222:223], v250
	ds_read_b64_tr_b16 v[224:225], v244
	ds_read_b64_tr_b16 v[226:227], v245
	ds_read_b64_tr_b16 v[200:201], v246
	ds_read_b64_tr_b16 v[202:203], v247
	ds_read_b64_tr_b16 v[228:229], v251 offset:4096
	ds_read_b64_tr_b16 v[230:231], v0 offset:4096
	ds_read_b64_tr_b16 v[232:233], v95 offset:4096
	ds_read_b64_tr_b16 v[234:235], v250 offset:4096
	ds_read_b64_tr_b16 v[236:237], v244 offset:4096
	ds_read_b64_tr_b16 v[238:239], v245 offset:4096
	ds_read_b64_tr_b16 v[240:241], v246 offset:4096
	ds_read_b64_tr_b16 v[242:243], v247 offset:4096
	s_cbranch_scc1 .LBB0_401
	s_cmp_eq_u32 s29, 2
	s_cselect_b64 s[0:1], -1, 0
	s_cbranch_execz .LBB0_402
	s_branch .LBB0_403

.LBB0_405:
	s_nop 5
	v_max_f32_e32 v0, v67, v67
	v_max_f32_e32 v95, v66, v66
	v_max_f32_e32 v0, v95, v0
	v_max3_f32 v0, v0, v68, v69
	v_max3_f32 v0, v0, v70, v71
	v_max3_f32 v0, v0, v72, v73
	v_max3_f32 v0, v0, v74, v75
	v_max3_f32 v0, v0, v76, v77
	v_max3_f32 v0, v0, v78, v79
	v_max3_f32 v0, v0, v80, v81
	v_mov_b32_e32 v95, v0
	s_nop 1
	v_permlane32_swap_b32_e32 v95, v0
	s_nop 0
	v_max3_f32 v95, v199, v0, v95
	v_sub_f32_e32 v0, v199, v95
	v_exp_f32_e32 v0, v0
	v_sub_f32_e32 v66, v66, v95
	v_sub_f32_e32 v67, v67, v95
	v_exp_f32_e32 v66, v66
	v_sub_f32_e32 v68, v68, v95
	v_exp_f32_e32 v67, v67
	v_sub_f32_e32 v69, v69, v95
	v_exp_f32_e32 v68, v68
	v_sub_f32_e32 v70, v70, v95
	v_add_f32_e32 v204, v67, v66
	v_exp_f32_e32 v69, v69
	v_sub_f32_e32 v71, v71, v95
	v_add_f32_e32 v204, v68, v204
	v_exp_f32_e32 v70, v70
	v_sub_f32_e32 v72, v72, v95
	v_add_f32_e32 v204, v69, v204
	v_exp_f32_e32 v71, v71
	v_sub_f32_e32 v73, v73, v95
	v_add_f32_e32 v204, v70, v204
	v_exp_f32_e32 v72, v72
	v_sub_f32_e32 v74, v74, v95
	v_add_f32_e32 v204, v71, v204
	v_exp_f32_e32 v73, v73
	v_sub_f32_e32 v75, v75, v95
	v_add_f32_e32 v204, v72, v204
	v_exp_f32_e32 v74, v74
	v_sub_f32_e32 v76, v76, v95
	v_add_f32_e32 v204, v73, v204
	v_exp_f32_e32 v75, v75
	v_sub_f32_e32 v77, v77, v95
	v_add_f32_e32 v204, v74, v204
	v_exp_f32_e32 v76, v76
	v_sub_f32_e32 v78, v78, v95
	v_add_f32_e32 v204, v75, v204
	v_exp_f32_e32 v77, v77
	v_sub_f32_e32 v79, v79, v95
	v_add_f32_e32 v204, v76, v204
	v_exp_f32_e32 v78, v78
	v_sub_f32_e32 v80, v80, v95
	v_add_f32_e32 v204, v77, v204
	v_exp_f32_e32 v79, v79
	v_sub_f32_e32 v81, v81, v95
	v_add_f32_e32 v204, v78, v204
	v_exp_f32_e32 v80, v80
	v_add_f32_e32 v204, v79, v204
	v_exp_f32_e32 v81, v81
	v_add_f32_e32 v204, v80, v204
	v_add_f32_e32 v204, v81, v204
	v_fmac_f32_e32 v204, v198, v0
	v_cvt_pk_bf16_f32 v244, v66, v67
	v_cvt_pk_bf16_f32 v245, v68, v69
	v_cvt_pk_bf16_f32 v246, v70, v71
	v_cvt_pk_bf16_f32 v247, v72, v73
	v_cvt_pk_bf16_f32 v66, v74, v75
	v_cvt_pk_bf16_f32 v67, v76, v77
	v_cvt_pk_bf16_f32 v68, v78, v79
	v_cvt_pk_bf16_f32 v69, v80, v81
	s_waitcnt lgkmcnt(8)
	v_pk_mul_f32 v[50:51], v[50:51], v[0:1] op_sel_hi:[1,0]
	v_pk_mul_f32 v[52:53], v[52:53], v[0:1] op_sel_hi:[1,0]
	v_pk_mul_f32 v[54:55], v[54:55], v[0:1] op_sel_hi:[1,0]
	v_pk_mul_f32 v[56:57], v[56:57], v[0:1] op_sel_hi:[1,0]
	v_pk_mul_f32 v[58:59], v[58:59], v[0:1] op_sel_hi:[1,0]
	v_pk_mul_f32 v[60:61], v[60:61], v[0:1] op_sel_hi:[1,0]
	v_pk_mul_f32 v[62:63], v[62:63], v[0:1] op_sel_hi:[1,0]
	v_pk_mul_f32 v[64:65], v[64:65], v[0:1] op_sel_hi:[1,0]
	v_pk_mul_f32 v[34:35], v[34:35], v[0:1] op_sel_hi:[1,0]
	v_pk_mul_f32 v[36:37], v[36:37], v[0:1] op_sel_hi:[1,0]
	v_mfma_f32_32x32x16_bf16 v[50:65], v[216:219], v[244:247], v[50:65]
	v_pk_mul_f32 v[38:39], v[38:39], v[0:1] op_sel_hi:[1,0]
	v_pk_mul_f32 v[40:41], v[40:41], v[0:1] op_sel_hi:[1,0]
	v_pk_mul_f32 v[42:43], v[42:43], v[0:1] op_sel_hi:[1,0]
	v_pk_mul_f32 v[44:45], v[44:45], v[0:1] op_sel_hi:[1,0]
	v_pk_mul_f32 v[46:47], v[46:47], v[0:1] op_sel_hi:[1,0]
	v_pk_mul_f32 v[48:49], v[48:49], v[0:1] op_sel_hi:[1,0]
	v_pk_mul_f32 v[18:19], v[18:19], v[0:1] op_sel_hi:[1,0]
	v_pk_mul_f32 v[20:21], v[20:21], v[0:1] op_sel_hi:[1,0]
	v_mfma_f32_32x32x16_bf16 v[34:49], v[220:223], v[244:247], v[34:49]
	v_pk_mul_f32 v[22:23], v[22:23], v[0:1] op_sel_hi:[1,0]
	v_pk_mul_f32 v[24:25], v[24:25], v[0:1] op_sel_hi:[1,0]
	v_pk_mul_f32 v[26:27], v[26:27], v[0:1] op_sel_hi:[1,0]
	v_pk_mul_f32 v[28:29], v[28:29], v[0:1] op_sel_hi:[1,0]
	v_pk_mul_f32 v[30:31], v[30:31], v[0:1] op_sel_hi:[1,0]
	v_pk_mul_f32 v[32:33], v[32:33], v[0:1] op_sel_hi:[1,0]
	v_pk_mul_f32 v[2:3], v[2:3], v[0:1] op_sel_hi:[1,0]
	v_pk_mul_f32 v[4:5], v[4:5], v[0:1] op_sel_hi:[1,0]
	v_mfma_f32_32x32x16_bf16 v[18:33], v[224:227], v[244:247], v[18:33]
	v_pk_mul_f32 v[6:7], v[6:7], v[0:1] op_sel_hi:[1,0]
	v_pk_mul_f32 v[8:9], v[8:9], v[0:1] op_sel_hi:[1,0]
	v_pk_mul_f32 v[10:11], v[10:11], v[0:1] op_sel_hi:[1,0]
	v_pk_mul_f32 v[12:13], v[12:13], v[0:1] op_sel_hi:[1,0]
	v_pk_mul_f32 v[14:15], v[14:15], v[0:1] op_sel_hi:[1,0]
	v_pk_mul_f32 v[16:17], v[16:17], v[0:1] op_sel_hi:[1,0]
	s_nop 1
	v_mfma_f32_32x32x16_bf16 v[2:17], v[200:203], v[244:247], v[2:17]
	s_waitcnt lgkmcnt(0)
	v_mfma_f32_32x32x16_bf16 v[50:65], v[228:231], v[66:69], v[50:65]
	v_mfma_f32_32x32x16_bf16 v[34:49], v[232:235], v[66:69], v[34:49]
	v_mfma_f32_32x32x16_bf16 v[18:33], v[236:239], v[66:69], v[18:33]
	v_mfma_f32_32x32x16_bf16 v[2:17], v[240:243], v[66:69], v[2:17]
	v_mov_b32_e32 v198, v204
	v_mov_b32_e32 v199, v95

.LBB0_441:
	v_and_b32_e32 v14, 31, v169
	v_lshrrev_b32_e32 v15, 5, v169
	v_lshlrev_b32_e32 v2, 2, v169
	v_and_b32_e32 v2, 12, v2
	v_bfe_u32 v3, v169, 2, 2
	v_or_b32_e32 v2, v2, v3
	v_xor_b32_e32 v250, v15, v2
	v_lshlrev_b32_e32 v250, 4, v250
	v_lshl_add_u32 v204, v14, 8, v250
	v_lshl_or_b32 v14, v15, 2, v3
	v_lshlrev_b32_e32 v2, 2, v3
	v_or_b32_e32 v2, v2, v15
	v_bfe_u32 v250, v169, 1, 1
	v_lshrrev_b32_e32 v251, 3, v169
	v_and_or_b32 v250, v251, 2, v250
	v_xor_b32_e32 v250, v250, v2
	v_lshlrev_b32_e32 v250, 4, v250
	v_lshl_add_u32 v250, v14, 8, v250
	v_lshlrev_b32_e32 v251, 3, v169
	v_and_b32_e32 v251, 8, v251
	v_add_u32_e32 v215, v250, v251
	v_add_u32_e32 v215, 0x2000, v215
	v_mov_b32_e32 v14, v1
	v_mov_b32_e32 v15, v1
	v_mov_b32_e32 v0, v1
	s_waitcnt lgkmcnt(0)
	v_mov_b32_e32 v2, v1
	v_mov_b32_e32 v3, v1
	v_mov_b32_e32 v4, v1
	v_mov_b32_e32 v5, v1
	v_mov_b32_e32 v6, v1
	v_mov_b32_e32 v7, v1
	v_mov_b32_e32 v8, v1
	v_mov_b32_e32 v9, v1
	v_mov_b32_e32 v10, v1
	v_mov_b32_e32 v11, v1
	v_mov_b32_e32 v12, v1
	v_mov_b32_e32 v13, v1
	v_mov_b64_e32 v[64:65], v[14:15]
	v_mov_b64_e32 v[48:49], v[14:15]
	v_mov_b64_e32 v[32:33], v[14:15]
	s_waitcnt vmcnt(0)
	v_mov_b64_e32 v[82:83], v[124:125]
	v_mov_b64_e32 v[86:87], v[120:121]
	v_mov_b64_e32 v[90:91], v[116:117]
	v_mov_b64_e32 v[130:131], v[114:115]
	v_mov_b64_e32 v[134:135], v[110:111]
	v_mov_b64_e32 v[138:139], v[106:107]
	v_mov_b64_e32 v[142:143], v[102:103]
	v_mov_b64_e32 v[146:147], v[98:99]
	s_bitcmp1_b32 s56, 0
	v_mov_b64_e32 v[62:63], v[12:13]
	v_mov_b64_e32 v[60:61], v[10:11]
	v_mov_b64_e32 v[58:59], v[8:9]
	v_mov_b64_e32 v[56:57], v[6:7]
	v_mov_b64_e32 v[54:55], v[4:5]
	v_mov_b64_e32 v[52:53], v[2:3]
	v_mov_b64_e32 v[50:51], v[0:1]
	v_mov_b64_e32 v[46:47], v[12:13]
	v_mov_b64_e32 v[44:45], v[10:11]
	v_mov_b64_e32 v[42:43], v[8:9]
	v_mov_b64_e32 v[40:41], v[6:7]
	v_mov_b64_e32 v[38:39], v[4:5]
	v_mov_b64_e32 v[36:37], v[2:3]
	v_mov_b64_e32 v[34:35], v[0:1]
	v_mov_b64_e32 v[30:31], v[12:13]
	v_mov_b64_e32 v[28:29], v[10:11]
	v_mov_b64_e32 v[26:27], v[8:9]
	v_mov_b64_e32 v[24:25], v[6:7]
	v_mov_b64_e32 v[22:23], v[4:5]
	v_mov_b64_e32 v[20:21], v[2:3]
	v_mov_b64_e32 v[18:19], v[0:1]
	v_mov_b64_e32 v[16:17], v[14:15]
	v_mov_b64_e32 v[84:85], v[126:127]
	v_mov_b64_e32 v[88:89], v[122:123]
	v_mov_b64_e32 v[92:93], v[118:119]
	v_mov_b64_e32 v[128:129], v[112:113]
	v_mov_b64_e32 v[132:133], v[108:109]
	v_mov_b64_e32 v[136:137], v[104:105]
	v_mov_b64_e32 v[140:141], v[100:101]
	v_mov_b64_e32 v[144:145], v[96:97]
	s_cselect_b64 s[10:11], -1, 0
	v_mov_b32_e32 v199, 0xc61c4000
	v_mov_b32_e32 v198, 0
	s_mov_b32 s24, 8
	s_mov_b64 s[26:27], s[4:5]
	s_mov_b64 s[12:13], s[86:87]
	v_mov_b32_e32 v94, v182
	v_mov_b32_e32 v183, v171
	s_mov_b32 s98, s61
	s_mov_b32 s50, s68
	s_mov_b32 s67, s51
	s_mov_b32 s69, s52
	s_mov_b32 s65, s57
	s_mov_b32 s53, s70
	s_mov_b32 s71, s60
	s_mov_b32 s19, s54
	s_mov_b32 s63, s55
	s_mov_b32 s59, s64
	v_mov_b64_e32 v[14:15], v[12:13]
	v_mov_b64_e32 v[12:13], v[10:11]
	v_mov_b64_e32 v[10:11], v[8:9]
	v_mov_b64_e32 v[8:9], v[6:7]
	v_mov_b64_e32 v[6:7], v[4:5]
	v_mov_b64_e32 v[4:5], v[2:3]
	v_mov_b64_e32 v[2:3], v[0:1]
	s_mov_b32 s21, 1
	s_and_b64 vcc, exec, s[10:11]
	s_cbranch_vccnz .LBB0_475
	s_branch .LBB0_443

.LBB0_475:
	s_lshl_b32 s0, s59, 14
	s_xor_b64 s[10:11], s[10:11], -1
	v_add_u32_e32 v201, s0, v204
	v_add_u32_e32 v202, s0, v215
	v_xor_b32_e32 v0, 32, v201
	v_xor_b32_e32 v95, 64, v201
	ds_read_b128 v[66:69], v201
	ds_read_b128 v[216:219], v0
	v_xor_b32_e32 v0, 0x60, v201
	ds_read_b128 v[220:223], v95
	v_xor_b32_e32 v95, 0x80, v201
	ds_read_b128 v[224:227], v0
	v_xor_b32_e32 v0, 0xa0, v201
	ds_read_b128 v[228:231], v95
	v_xor_b32_e32 v95, 0xc0, v201
	ds_read_b128 v[232:235], v0
	v_xor_b32_e32 v0, 0xe0, v201
	ds_read_b128 v[236:239], v95
	ds_read_b128 v[240:243], v0
	s_waitcnt lgkmcnt(7)
	v_mfma_f32_32x32x16_bf16 v[66:81], v[66:69], v[82:85], 0
	v_and_b32_e32 v251, 64, v207
	v_xor_b32_e32 v250, 32, v207
	v_add_u32_e32 v251, 64, v251
	v_cmp_lt_i32_e32 vcc, v250, v251
	s_nop 1
	v_cndmask_b32_e32 v250, v207, v250, vcc
	v_lshlrev_b32_e32 v200, 2, v250
	s_waitcnt lgkmcnt(6)
	v_mfma_f32_32x32x16_bf16 v[66:81], v[216:219], v[86:89], v[66:81]
	s_waitcnt lgkmcnt(5)
	v_mfma_f32_32x32x16_bf16 v[66:81], v[220:223], v[90:93], v[66:81]
	s_waitcnt lgkmcnt(4)
	v_mfma_f32_32x32x16_bf16 v[66:81], v[224:227], v[128:131], v[66:81]
	s_waitcnt lgkmcnt(3)
	v_mfma_f32_32x32x16_bf16 v[66:81], v[228:231], v[132:135], v[66:81]
	s_waitcnt lgkmcnt(2)
	v_mfma_f32_32x32x16_bf16 v[66:81], v[232:235], v[136:139], v[66:81]
	s_waitcnt lgkmcnt(1)
	v_mfma_f32_32x32x16_bf16 v[66:81], v[236:239], v[140:143], v[66:81]
	s_waitcnt lgkmcnt(0)
	v_mfma_f32_32x32x16_bf16 v[66:81], v[240:243], v[144:147], v[66:81]
	v_xor_b32_e32 v0, 0x820, v202
	v_xor_b32_e32 v95, 64, v202
	v_xor_b32_e32 v203, 0x860, v202
	v_xor_b32_e32 v244, 0x80, v202
	v_xor_b32_e32 v245, 0x8a0, v202
	v_xor_b32_e32 v246, 0xc0, v202
	v_xor_b32_e32 v247, 0x8e0, v202
	ds_read_b64_tr_b16 v[216:217], v202
	ds_read_b64_tr_b16 v[218:219], v0
	ds_read_b64_tr_b16 v[220:221], v95
	ds_read_b64_tr_b16 v[222:223], v203
	ds_read_b64_tr_b16 v[224:225], v244
	ds_read_b64_tr_b16 v[226:227], v245
	ds_read_b64_tr_b16 v[248:249], v246
	ds_read_b64_tr_b16 v[250:251], v247
	ds_read_b64_tr_b16 v[228:229], v202 offset:4096
	ds_read_b64_tr_b16 v[230:231], v0 offset:4096
	ds_read_b64_tr_b16 v[232:233], v95 offset:4096
	ds_read_b64_tr_b16 v[234:235], v203 offset:4096
	ds_read_b64_tr_b16 v[236:237], v244 offset:4096
	ds_read_b64_tr_b16 v[238:239], v245 offset:4096
	ds_read_b64_tr_b16 v[240:241], v246 offset:4096
	ds_read_b64_tr_b16 v[242:243], v247 offset:4096
	v_max_f32_e32 v0, v67, v67
	v_max_f32_e32 v95, v66, v66
	v_max_f32_e32 v0, v95, v0
	v_max3_f32 v0, v0, v68, v69
	v_max3_f32 v0, v0, v70, v71
	v_max3_f32 v0, v0, v72, v73
	v_max3_f32 v0, v0, v74, v75
	v_max3_f32 v0, v0, v76, v77
	v_max3_f32 v0, v0, v78, v79
	v_max3_f32 v0, v0, v80, v81
	v_mov_b32_e32 v95, v0
	s_nop 1
	v_permlane32_swap_b32_e32 v95, v0
	s_nop 0
	v_max3_f32 v95, v199, v0, v95
	v_sub_f32_e32 v0, v199, v95
	v_exp_f32_e32 v0, v0
	v_sub_f32_e32 v66, v66, v95
	v_sub_f32_e32 v67, v67, v95
	v_exp_f32_e32 v66, v66
	v_sub_f32_e32 v68, v68, v95
	v_exp_f32_e32 v67, v67
	v_sub_f32_e32 v69, v69, v95
	v_exp_f32_e32 v68, v68
	v_sub_f32_e32 v70, v70, v95
	v_add_f32_e32 v201, v67, v66
	v_exp_f32_e32 v69, v69
	v_sub_f32_e32 v71, v71, v95
	v_add_f32_e32 v201, v68, v201
	v_exp_f32_e32 v70, v70
	v_sub_f32_e32 v72, v72, v95
	v_add_f32_e32 v201, v69, v201
	v_exp_f32_e32 v71, v71
	v_sub_f32_e32 v73, v73, v95
	v_add_f32_e32 v201, v70, v201
	v_exp_f32_e32 v72, v72
	v_sub_f32_e32 v74, v74, v95
	v_add_f32_e32 v201, v71, v201
	v_exp_f32_e32 v73, v73
	v_sub_f32_e32 v75, v75, v95
	v_add_f32_e32 v201, v72, v201
	v_exp_f32_e32 v74, v74
	v_sub_f32_e32 v76, v76, v95
	v_add_f32_e32 v201, v73, v201
	v_exp_f32_e32 v75, v75
	v_sub_f32_e32 v77, v77, v95
	v_add_f32_e32 v201, v74, v201
	v_exp_f32_e32 v76, v76
	v_sub_f32_e32 v78, v78, v95
	v_add_f32_e32 v201, v75, v201
	v_exp_f32_e32 v77, v77
	v_sub_f32_e32 v79, v79, v95
	v_add_f32_e32 v201, v76, v201
	v_exp_f32_e32 v78, v78
	v_sub_f32_e32 v80, v80, v95
	v_add_f32_e32 v201, v77, v201
	v_exp_f32_e32 v79, v79
	v_sub_f32_e32 v81, v81, v95
	v_add_f32_e32 v201, v78, v201
	v_exp_f32_e32 v80, v80
	v_add_f32_e32 v201, v79, v201
	v_exp_f32_e32 v81, v81
	v_add_f32_e32 v201, v80, v201
	v_add_f32_e32 v201, v81, v201
	v_fmac_f32_e32 v201, v198, v0
	v_cvt_pk_bf16_f32 v244, v66, v67
	v_cvt_pk_bf16_f32 v245, v68, v69
	v_cvt_pk_bf16_f32 v246, v70, v71
	v_cvt_pk_bf16_f32 v247, v72, v73
	v_cvt_pk_bf16_f32 v66, v74, v75
	v_cvt_pk_bf16_f32 v67, v76, v77
	v_cvt_pk_bf16_f32 v68, v78, v79
	v_cvt_pk_bf16_f32 v69, v80, v81
	s_waitcnt lgkmcnt(8)
	v_pk_mul_f32 v[50:51], v[50:51], v[0:1] op_sel_hi:[1,0]
	v_pk_mul_f32 v[52:53], v[52:53], v[0:1] op_sel_hi:[1,0]
	v_pk_mul_f32 v[54:55], v[54:55], v[0:1] op_sel_hi:[1,0]
	v_pk_mul_f32 v[56:57], v[56:57], v[0:1] op_sel_hi:[1,0]
	v_pk_mul_f32 v[58:59], v[58:59], v[0:1] op_sel_hi:[1,0]
	v_pk_mul_f32 v[60:61], v[60:61], v[0:1] op_sel_hi:[1,0]
	v_pk_mul_f32 v[62:63], v[62:63], v[0:1] op_sel_hi:[1,0]
	v_pk_mul_f32 v[64:65], v[64:65], v[0:1] op_sel_hi:[1,0]
	v_pk_mul_f32 v[34:35], v[34:35], v[0:1] op_sel_hi:[1,0]
	v_pk_mul_f32 v[36:37], v[36:37], v[0:1] op_sel_hi:[1,0]
	v_mfma_f32_32x32x16_bf16 v[50:65], v[216:219], v[244:247], v[50:65]
	v_pk_mul_f32 v[38:39], v[38:39], v[0:1] op_sel_hi:[1,0]
	v_pk_mul_f32 v[40:41], v[40:41], v[0:1] op_sel_hi:[1,0]
	v_pk_mul_f32 v[42:43], v[42:43], v[0:1] op_sel_hi:[1,0]
	v_pk_mul_f32 v[44:45], v[44:45], v[0:1] op_sel_hi:[1,0]
	v_pk_mul_f32 v[46:47], v[46:47], v[0:1] op_sel_hi:[1,0]
	v_pk_mul_f32 v[48:49], v[48:49], v[0:1] op_sel_hi:[1,0]
	v_pk_mul_f32 v[18:19], v[18:19], v[0:1] op_sel_hi:[1,0]
	v_pk_mul_f32 v[20:21], v[20:21], v[0:1] op_sel_hi:[1,0]
	v_mfma_f32_32x32x16_bf16 v[34:49], v[220:223], v[244:247], v[34:49]
	v_pk_mul_f32 v[22:23], v[22:23], v[0:1] op_sel_hi:[1,0]
	v_pk_mul_f32 v[24:25], v[24:25], v[0:1] op_sel_hi:[1,0]
	v_pk_mul_f32 v[26:27], v[26:27], v[0:1] op_sel_hi:[1,0]
	v_pk_mul_f32 v[28:29], v[28:29], v[0:1] op_sel_hi:[1,0]
	v_pk_mul_f32 v[30:31], v[30:31], v[0:1] op_sel_hi:[1,0]
	v_pk_mul_f32 v[32:33], v[32:33], v[0:1] op_sel_hi:[1,0]
	v_pk_mul_f32 v[2:3], v[2:3], v[0:1] op_sel_hi:[1,0]
	v_pk_mul_f32 v[4:5], v[4:5], v[0:1] op_sel_hi:[1,0]
	v_mfma_f32_32x32x16_bf16 v[18:33], v[224:227], v[244:247], v[18:33]
	v_pk_mul_f32 v[6:7], v[6:7], v[0:1] op_sel_hi:[1,0]
	v_pk_mul_f32 v[8:9], v[8:9], v[0:1] op_sel_hi:[1,0]
	v_pk_mul_f32 v[10:11], v[10:11], v[0:1] op_sel_hi:[1,0]
	v_pk_mul_f32 v[12:13], v[12:13], v[0:1] op_sel_hi:[1,0]
	v_pk_mul_f32 v[14:15], v[14:15], v[0:1] op_sel_hi:[1,0]
	v_pk_mul_f32 v[16:17], v[16:17], v[0:1] op_sel_hi:[1,0]
	s_nop 1
	v_mfma_f32_32x32x16_bf16 v[2:17], v[248:251], v[244:247], v[2:17]
	s_waitcnt lgkmcnt(0)
	v_mfma_f32_32x32x16_bf16 v[50:65], v[228:231], v[66:69], v[50:65]
	v_mfma_f32_32x32x16_bf16 v[34:49], v[232:235], v[66:69], v[34:49]
	v_mfma_f32_32x32x16_bf16 v[18:33], v[236:239], v[66:69], v[18:33]
	v_mfma_f32_32x32x16_bf16 v[2:17], v[240:243], v[66:69], v[2:17]
	v_mov_b32_e32 v198, v201
	v_mov_b32_e32 v199, v95
	v_mov_b32_e32 v68, v201
	s_mov_b64 s[0:1], -1
	s_andn2_b64 vcc, exec, s[10:11]
	s_cbranch_vccnz .LBB0_479
	s_waitcnt vmcnt(4)
	s_mov_b64 s[0:1], 0

.LBB0_481:
	s_add_i32 s0, s59, 1
	s_cmp_lg_u32 s0, 6
	s_cselect_b32 s59, s0, 0
	s_bitcmp1_b32 s21, 0
	s_waitcnt lgkmcnt(0)
	s_barrier
	s_cselect_b64 s[10:11], -1, 0
	s_add_i32 s24, s24, -1
	s_cmp_eq_u32 s24, 0
	s_cbranch_scc0 .LBB0_442
	ds_bpermute_b32 v69, v200, v68
	s_cmp_gt_i32 s7, -1
	s_cbranch_scc0 .LBB0_496
	s_add_i32 s0, s7, s82
	s_add_i32 s1, s0, -3
	s_cmp_gt_i32 s0, 2
	s_cselect_b32 s0, s1, s0
	s_cmp_eq_u32 s0, 1
	s_cselect_b32 s1, 1, 2
	s_cmp_lg_u32 s0, 0
	s_cselect_b32 s1, s1, 0
	s_cmp_lt_i32 s1, 1
	s_mov_b64 s[10:11], -1
	s_cbranch_scc1 .LBB0_493
	s_cmp_lg_u32 s1, 1
	s_cbranch_scc0 .LBB0_490
	s_mul_hi_i32 s0, s62, 0x2aaaaaab
	s_lshr_b32 s1, s0, 31
	s_ashr_i32 s0, s0, 7
	s_add_i32 s0, s0, s1
	s_add_i32 s16, s0, 1
	s_mulk_i32 s0, 0x300
	s_sub_i32 s0, s62, s0
	s_sext_i32_i16 s1, s0
	s_mulk_i32 s1, 0x2aab
	s_lshr_b32 s10, s1, 31
	s_ashr_i32 s1, s1, 19
	s_add_i32 s1, s1, s10
	s_mul_i32 s10, s1, 48
	s_sub_i32 s0, s0, s10
	s_sext_i32_i16 s14, s0
	s_and_b32 s15, s14, 7
	s_mov_b64 s[10:11], -1
	s_cmp_lg_u32 s16, 2
	s_sext_i32_i16 s0, s1
	s_cbranch_scc0 .LBB0_487
	s_add_i32 s1, s62, 0x2ff
	s_lshr_b32 s10, s15, 1
	s_and_b32 s11, s14, 1
	s_cmpk_lt_u32 s1, 0x5ff
	s_cselect_b32 s17, s10, 0
	s_cselect_b32 s20, s11, s15
	s_ashr_i32 s1, s0, 31
	s_lshl_b64 s[10:11], s[0:1], 11
	s_cmp_eq_u32 s16, 0
	v_lshl_add_u32 v66, s20, 8, v173
	v_ashrrev_i32_e32 v67, 31, v66
	s_cselect_b32 s1, 0, 2
	v_lshlrev_b64 v[66:67], s1, v[66:67]
	s_or_b32 s10, s10, s17
	v_lshl_add_u64 v[66:67], s[10:11], 0, v[66:67]
	s_mov_b64 s[10:11], 0

.LBB0_497:
	s_mul_hi_i32 s0, s58, 0x2aaaaaab
	s_lshr_b32 s1, s0, 31
	s_ashr_i32 s0, s0, 3
	s_add_i32 s20, s0, s1
	s_mul_i32 s0, s20, 48
	s_sub_i32 s10, s58, s0
	s_lshl_b32 s1, s10, 2
	s_and_b32 s0, s1, 28
	v_sub_u32_e64 v0, s0, 1 clamp
	s_max_u32 s19, s0, 4
	v_readfirstlane_b32 s11, v0
	s_min_u32 s21, s11, 24
	v_readlane_b32 s11, v254, 28
	s_or_b32 s16, s0, s11
	s_ashr_i32 s17, s10, 3
	s_sub_i32 s10, s21, s19
	s_cmp_lt_i32 s10, -11
	s_waitcnt vmcnt(0) lgkmcnt(0)
	s_cbranch_scc1 .LBB0_607
	v_sub_u32_e64 v0, s16, 4 clamp
	v_min_u32_e32 v130, 24, v0
	v_add_u32_e32 v0, s0, v196
	v_sub_u32_e64 v2, s16, 3 clamp
	s_mul_i32 s10, s17, 0x744
	s_mul_i32 s11, s19, 0x7c
	s_bfe_u32 s1, s1, 0x30002
	v_sub_u32_e64 v0, v0, 4 clamp
	v_min_u32_e32 v2, 24, v2
	s_add_i32 s10, s10, s11
	s_mulk_i32 s1, 0x1f0
	v_min_u32_e32 v0, 24, v0
	v_mov_b32_e32 v14, v1
	v_mov_b32_e32 v15, v1
	v_add_u32_e32 v129, 8, v2
	s_sub_i32 s1, s10, s1
	v_sub_u32_e32 v132, -4, v0
	v_mov_b32_e32 v0, v1
	v_mov_b32_e32 v2, v1
	v_mov_b32_e32 v3, v1
	v_mov_b32_e32 v4, v1
	v_mov_b32_e32 v5, v1
	v_mov_b32_e32 v6, v1
	v_mov_b32_e32 v7, v1
	v_mov_b32_e32 v8, v1
	v_mov_b32_e32 v9, v1
	v_mov_b32_e32 v10, v1
	v_mov_b32_e32 v11, v1
	v_mov_b32_e32 v12, v1
	v_mov_b32_e32 v13, v1
	v_mov_b64_e32 v[78:79], v[14:15]
	v_mov_b64_e32 v[62:63], v[14:15]
	v_mov_b64_e32 v[46:47], v[14:15]
	v_mov_b64_e32 v[30:31], v[14:15]
	s_add_i32 s21, s21, 12
	v_add_u32_e32 v131, s1, v195
	v_mov_b32_e32 v133, 0xc61c4000
	v_mov_b32_e32 v128, 0
	s_mov_b32 s98, s61
	v_mov_b64_e32 v[76:77], v[12:13]
	v_mov_b64_e32 v[74:75], v[10:11]
	v_mov_b64_e32 v[72:73], v[8:9]
	v_mov_b64_e32 v[70:71], v[6:7]
	v_mov_b64_e32 v[68:69], v[4:5]
	v_mov_b64_e32 v[66:67], v[2:3]
	v_mov_b64_e32 v[64:65], v[0:1]
	v_mov_b64_e32 v[60:61], v[12:13]
	v_mov_b64_e32 v[58:59], v[10:11]
	v_mov_b64_e32 v[56:57], v[8:9]
	v_mov_b64_e32 v[54:55], v[6:7]
	v_mov_b64_e32 v[52:53], v[4:5]
	v_mov_b64_e32 v[50:51], v[2:3]
	v_mov_b64_e32 v[48:49], v[0:1]
	v_mov_b64_e32 v[44:45], v[12:13]
	v_mov_b64_e32 v[42:43], v[10:11]
	v_mov_b64_e32 v[40:41], v[8:9]
	v_mov_b64_e32 v[38:39], v[6:7]
	v_mov_b64_e32 v[36:37], v[4:5]
	v_mov_b64_e32 v[34:35], v[2:3]
	v_mov_b64_e32 v[32:33], v[0:1]
	v_mov_b64_e32 v[28:29], v[12:13]
	v_mov_b64_e32 v[26:27], v[10:11]
	v_mov_b64_e32 v[24:25], v[8:9]
	v_mov_b64_e32 v[22:23], v[6:7]
	v_mov_b64_e32 v[20:21], v[4:5]
	v_mov_b64_e32 v[18:19], v[2:3]
	v_mov_b64_e32 v[16:17], v[0:1]
	v_and_b32_e32 v232, 31, v169
	v_add_u32_e32 v232, s18, v232
	v_lshrrev_b32_e32 v233, 5, v169
	v_lshlrev_b32_e32 v234, 2, v232
	v_and_b32_e32 v234, 12, v234
	v_bfe_u32 v235, v232, 2, 2
	v_or_b32_e32 v234, v234, v235
	v_xor_b32_e32 v234, v233, v234
	v_lshlrev_b32_e32 v234, 4, v234
	v_lshl_add_u32 v248, v232, 8, v234
	v_lshl_add_u32 v232, v233, 2, s18
	v_lshrrev_b32_e32 v234, 2, v169
	v_and_or_b32 v232, v234, 3, v232
	v_bfe_u32 v234, v169, 1, 1
	v_lshrrev_b32_e32 v235, 3, v169
	v_and_or_b32 v234, v235, 2, v234
	v_lshlrev_b32_e32 v235, 3, v169
	v_and_b32_e32 v235, 8, v235
	v_lshlrev_b32_e32 v236, 2, v232
	v_and_b32_e32 v236, 12, v236
	v_bfe_u32 v251, v232, 2, 2
	v_or_b32_e32 v236, v236, v251
	v_xor_b32_e32 v236, v234, v236
	v_lshlrev_b32_e32 v236, 4, v236
	v_lshl_add_u32 v236, v232, 8, v236
	v_add_u32_e32 v249, v236, v235
	v_add_u32_e32 v232, 8, v232
	v_lshlrev_b32_e32 v236, 2, v232
	v_and_b32_e32 v236, 12, v236
	v_bfe_u32 v251, v232, 2, 2
	v_or_b32_e32 v236, v236, v251
	v_xor_b32_e32 v236, v234, v236
	v_lshlrev_b32_e32 v236, 4, v236
	v_lshl_add_u32 v236, v232, 8, v236
	v_add_u32_e32 v250, v236, v235

.LBB0_565:
	s_add_i32 s0, s19, -4
	v_cmp_ge_u32_e32 vcc, s0, v130
	v_cmp_lt_u32_e64 s[12:13], s0, v129
	s_and_b64 s[0:1], vcc, s[12:13]
	s_andn2_b64 vcc, exec, s[0:1]
	s_cbranch_vccnz .LBB0_602
	s_lshl_b32 s0, s64, 14
	s_add_i32 s1, s64, 1
	s_cmp_lg_u32 s1, 6
	s_cselect_b32 s1, s1, 0
	s_lshl_b32 s1, s1, 14
	v_add_u32_e32 v251, s0, v248
	v_xor_b32_e32 v0, 32, v251
	v_xor_b32_e32 v2, 64, v251
	ds_read_b128 v[4:7], v251
	ds_read_b128 v[8:11], v0
	v_xor_b32_e32 v0, 0x60, v251
	ds_read_b128 v[12:15], v2
	v_xor_b32_e32 v2, 0x80, v251
	ds_read_b128 v[134:137], v0
	v_xor_b32_e32 v0, 0xa0, v251
	ds_read_b128 v[138:141], v2
	v_xor_b32_e32 v2, 0xc0, v251
	ds_read_b128 v[142:145], v0
	v_xor_b32_e32 v0, 0xe0, v251
	ds_read_b128 v[198:201], v2
	ds_read_b128 v[216:219], v0
	ds_read2_b32 v[232:233], v131 offset1:1
	ds_read2_b32 v[234:235], v131 offset0:2 offset1:3
	ds_read2_b32 v[236:237], v131 offset0:8 offset1:9
	ds_read2_b32 v[238:239], v131 offset0:10 offset1:11
	ds_read2_b32 v[240:241], v131 offset0:16 offset1:17
	ds_read2_b32 v[242:243], v131 offset0:18 offset1:19
	ds_read2_b32 v[244:245], v131 offset0:24 offset1:25
	s_waitcnt lgkmcnt(14)
	v_mfma_f32_32x32x16_bf16 v[80:95], v[4:7], v[124:127], 0
	ds_read2_b32 v[246:247], v131 offset0:26 offset1:27
	v_add_u32_e32 v0, s19, v132
	v_cmp_gt_u32_e32 vcc, 8, v0
	v_add_u32_e32 v2, s1, v249
	v_add_u32_e32 v3, s1, v250
	v_cndmask_b32_e32 v0, v212, v187, vcc
	s_waitcnt lgkmcnt(14)
	v_mfma_f32_32x32x16_bf16 v[80:95], v[8:11], v[120:123], v[80:95]
	s_waitcnt lgkmcnt(13)
	v_mfma_f32_32x32x16_bf16 v[80:95], v[12:15], v[116:119], v[80:95]
	s_waitcnt lgkmcnt(12)
	v_mfma_f32_32x32x16_bf16 v[80:95], v[134:137], v[112:115], v[80:95]
	s_waitcnt lgkmcnt(11)
	v_mfma_f32_32x32x16_bf16 v[80:95], v[138:141], v[108:111], v[80:95]
	s_waitcnt lgkmcnt(10)
	v_mfma_f32_32x32x16_bf16 v[80:95], v[142:145], v[104:107], v[80:95]
	s_waitcnt lgkmcnt(9)
	v_mfma_f32_32x32x16_bf16 v[80:95], v[198:201], v[100:103], v[80:95]
	s_waitcnt lgkmcnt(8)
	v_mfma_f32_32x32x16_bf16 v[80:95], v[216:219], v[96:99], v[80:95]
	v_xor_b32_e32 v4, 64, v2
	v_xor_b32_e32 v5, 64, v3
	v_xor_b32_e32 v6, 0x80, v2
	v_xor_b32_e32 v7, 0x80, v3
	v_xor_b32_e32 v8, 0xc0, v2
	v_xor_b32_e32 v9, 0xc0, v3
	ds_read_b64_tr_b16 v[220:221], v2
	ds_read_b64_tr_b16 v[222:223], v3
	ds_read_b64_tr_b16 v[224:225], v4
	ds_read_b64_tr_b16 v[226:227], v5
	ds_read_b64_tr_b16 v[228:229], v6
	ds_read_b64_tr_b16 v[230:231], v7
	ds_read_b64_tr_b16 v[198:199], v8
	ds_read_b64_tr_b16 v[200:201], v9
	s_waitcnt lgkmcnt(8)
	v_cmp_gt_u32_e32 vcc, 16, v0
	v_add_f32_e32 v232, v80, v232
	v_add_u32_e32 v251, 1, v0
	v_cmp_gt_u32_e64 s[0:1], 16, v251
	v_add_f32_e32 v233, v81, v233
	v_cndmask_b32_e32 v80, v210, v232, vcc
	v_add_u32_e32 v251, 2, v0
	v_cmp_gt_u32_e32 vcc, 16, v251
	v_add_f32_e32 v234, v82, v234
	v_cndmask_b32_e64 v81, v210, v233, s[0:1]
	v_add_u32_e32 v251, 3, v0
	v_cmp_gt_u32_e64 s[0:1], 16, v251
	v_add_f32_e32 v235, v83, v235
	v_cndmask_b32_e32 v82, v210, v234, vcc
	v_add_u32_e32 v251, 8, v0
	v_cmp_gt_u32_e32 vcc, 16, v251
	v_add_f32_e32 v236, v84, v236
	v_cndmask_b32_e64 v83, v210, v235, s[0:1]
	v_add_u32_e32 v251, 9, v0
	v_cmp_gt_u32_e64 s[0:1], 16, v251
	v_add_f32_e32 v237, v85, v237
	v_cndmask_b32_e32 v84, v210, v236, vcc
	v_add_u32_e32 v251, 10, v0
	v_cmp_gt_u32_e32 vcc, 16, v251
	v_add_f32_e32 v238, v86, v238
	v_cndmask_b32_e64 v85, v210, v237, s[0:1]
	v_add_u32_e32 v251, 11, v0
	v_cmp_gt_u32_e64 s[0:1], 16, v251
	v_add_f32_e32 v239, v87, v239
	v_cndmask_b32_e32 v86, v210, v238, vcc
	v_add_u32_e32 v251, 16, v0
	v_cmp_gt_u32_e32 vcc, 16, v251
	v_add_f32_e32 v240, v88, v240
	v_cndmask_b32_e64 v87, v210, v239, s[0:1]
	v_add_u32_e32 v251, 17, v0
	v_cmp_gt_u32_e64 s[0:1], 16, v251
	v_add_f32_e32 v241, v89, v241
	v_cndmask_b32_e32 v88, v210, v240, vcc
	v_add_u32_e32 v251, 18, v0
	v_cmp_gt_u32_e32 vcc, 16, v251
	v_add_f32_e32 v242, v90, v242
	v_cndmask_b32_e64 v89, v210, v241, s[0:1]
	v_add_u32_e32 v251, 19, v0
	v_cmp_gt_u32_e64 s[0:1], 16, v251
	v_add_f32_e32 v243, v91, v243
	v_cndmask_b32_e32 v90, v210, v242, vcc
	v_add_u32_e32 v251, 24, v0
	v_cmp_gt_u32_e32 vcc, 16, v251
	v_add_f32_e32 v244, v92, v244
	v_cndmask_b32_e64 v91, v210, v243, s[0:1]
	v_add_u32_e32 v251, 25, v0
	v_cmp_gt_u32_e64 s[0:1], 16, v251
	v_add_f32_e32 v245, v93, v245
	v_cndmask_b32_e32 v92, v210, v244, vcc
	v_add_u32_e32 v251, 26, v0
	v_cmp_gt_u32_e32 vcc, 16, v251
	v_add_f32_e32 v246, v94, v246
	v_cndmask_b32_e64 v93, v210, v245, s[0:1]
	v_add_u32_e32 v251, 27, v0
	v_cmp_gt_u32_e64 s[0:1], 16, v251
	v_add_f32_e32 v247, v95, v247
	v_cndmask_b32_e32 v94, v210, v246, vcc
	s_nop 1
	v_cndmask_b32_e64 v95, v210, v247, s[0:1]
	ds_read_b64_tr_b16 v[232:233], v2 offset:4096
	ds_read_b64_tr_b16 v[234:235], v3 offset:4096
	ds_read_b64_tr_b16 v[236:237], v4 offset:4096
	ds_read_b64_tr_b16 v[238:239], v5 offset:4096
	ds_read_b64_tr_b16 v[240:241], v6 offset:4096
	ds_read_b64_tr_b16 v[242:243], v7 offset:4096
	ds_read_b64_tr_b16 v[244:245], v8 offset:4096
	ds_read_b64_tr_b16 v[246:247], v9 offset:4096
	v_max_f32_e32 v0, v81, v81
	v_max_f32_e32 v4, v80, v80
	v_max_f32_e32 v0, v4, v0
	v_max3_f32 v0, v0, v82, v83
	v_max3_f32 v0, v0, v84, v85
	v_max3_f32 v0, v0, v86, v87
	v_max3_f32 v0, v0, v88, v89
	v_max3_f32 v0, v0, v90, v91
	v_max3_f32 v0, v0, v92, v93
	v_max3_f32 v0, v0, v94, v95
	v_mov_b32_e32 v4, v0
	s_nop 1
	v_permlane32_swap_b32_e32 v4, v0
	s_nop 0
	v_max3_f32 v4, v133, v0, v4
	v_sub_f32_e32 v0, v133, v4
	v_exp_f32_e32 v0, v0
	v_sub_f32_e32 v80, v80, v4
	v_sub_f32_e32 v81, v81, v4
	v_exp_f32_e32 v80, v80
	v_sub_f32_e32 v82, v82, v4
	v_exp_f32_e32 v81, v81
	v_sub_f32_e32 v83, v83, v4
	v_exp_f32_e32 v82, v82
	v_sub_f32_e32 v84, v84, v4
	v_add_f32_e32 v215, v81, v80
	v_exp_f32_e32 v83, v83
	v_sub_f32_e32 v85, v85, v4
	v_add_f32_e32 v215, v82, v215
	v_exp_f32_e32 v84, v84
	v_sub_f32_e32 v86, v86, v4
	v_add_f32_e32 v215, v83, v215
	v_exp_f32_e32 v85, v85
	v_sub_f32_e32 v87, v87, v4
	v_add_f32_e32 v215, v84, v215
	v_exp_f32_e32 v86, v86
	v_sub_f32_e32 v88, v88, v4
	v_add_f32_e32 v215, v85, v215
	v_exp_f32_e32 v87, v87
	v_sub_f32_e32 v89, v89, v4
	v_add_f32_e32 v215, v86, v215
	v_exp_f32_e32 v88, v88
	v_sub_f32_e32 v90, v90, v4
	v_add_f32_e32 v215, v87, v215
	v_exp_f32_e32 v89, v89
	v_sub_f32_e32 v91, v91, v4
	v_add_f32_e32 v215, v88, v215
	v_exp_f32_e32 v90, v90
	v_sub_f32_e32 v92, v92, v4
	v_add_f32_e32 v215, v89, v215
	v_exp_f32_e32 v91, v91
	v_sub_f32_e32 v93, v93, v4
	v_add_f32_e32 v215, v90, v215
	v_exp_f32_e32 v92, v92
	v_sub_f32_e32 v94, v94, v4
	v_add_f32_e32 v215, v91, v215
	v_exp_f32_e32 v93, v93
	v_sub_f32_e32 v95, v95, v4
	v_add_f32_e32 v215, v92, v215
	v_exp_f32_e32 v94, v94
	v_add_f32_e32 v215, v93, v215
	v_exp_f32_e32 v95, v95
	v_add_f32_e32 v215, v94, v215
	v_add_f32_e32 v215, v95, v215
	v_fmac_f32_e32 v215, v128, v0
	v_cvt_pk_bf16_f32 v8, v80, v81
	v_cvt_pk_bf16_f32 v9, v82, v83
	v_cvt_pk_bf16_f32 v10, v84, v85
	v_cvt_pk_bf16_f32 v11, v86, v87
	v_cvt_pk_bf16_f32 v12, v88, v89
	v_cvt_pk_bf16_f32 v13, v90, v91
	v_cvt_pk_bf16_f32 v14, v92, v93
	v_cvt_pk_bf16_f32 v15, v94, v95
	s_waitcnt lgkmcnt(8)
	v_pk_mul_f32 v[64:65], v[64:65], v[0:1] op_sel_hi:[1,0]
	v_pk_mul_f32 v[66:67], v[66:67], v[0:1] op_sel_hi:[1,0]
	v_pk_mul_f32 v[68:69], v[68:69], v[0:1] op_sel_hi:[1,0]
	v_pk_mul_f32 v[70:71], v[70:71], v[0:1] op_sel_hi:[1,0]
	v_pk_mul_f32 v[72:73], v[72:73], v[0:1] op_sel_hi:[1,0]
	v_pk_mul_f32 v[74:75], v[74:75], v[0:1] op_sel_hi:[1,0]
	v_pk_mul_f32 v[76:77], v[76:77], v[0:1] op_sel_hi:[1,0]
	v_pk_mul_f32 v[78:79], v[78:79], v[0:1] op_sel_hi:[1,0]
	v_pk_mul_f32 v[48:49], v[48:49], v[0:1] op_sel_hi:[1,0]
	v_pk_mul_f32 v[50:51], v[50:51], v[0:1] op_sel_hi:[1,0]
	v_mfma_f32_32x32x16_bf16 v[64:79], v[220:223], v[8:11], v[64:79]
	v_pk_mul_f32 v[52:53], v[52:53], v[0:1] op_sel_hi:[1,0]
	v_pk_mul_f32 v[54:55], v[54:55], v[0:1] op_sel_hi:[1,0]
	v_pk_mul_f32 v[56:57], v[56:57], v[0:1] op_sel_hi:[1,0]
	v_pk_mul_f32 v[58:59], v[58:59], v[0:1] op_sel_hi:[1,0]
	v_pk_mul_f32 v[60:61], v[60:61], v[0:1] op_sel_hi:[1,0]
	v_pk_mul_f32 v[62:63], v[62:63], v[0:1] op_sel_hi:[1,0]
	v_pk_mul_f32 v[32:33], v[32:33], v[0:1] op_sel_hi:[1,0]
	v_pk_mul_f32 v[34:35], v[34:35], v[0:1] op_sel_hi:[1,0]
	v_mfma_f32_32x32x16_bf16 v[48:63], v[224:227], v[8:11], v[48:63]
	v_pk_mul_f32 v[36:37], v[36:37], v[0:1] op_sel_hi:[1,0]
	v_pk_mul_f32 v[38:39], v[38:39], v[0:1] op_sel_hi:[1,0]
	v_pk_mul_f32 v[40:41], v[40:41], v[0:1] op_sel_hi:[1,0]
	v_pk_mul_f32 v[42:43], v[42:43], v[0:1] op_sel_hi:[1,0]
	v_pk_mul_f32 v[44:45], v[44:45], v[0:1] op_sel_hi:[1,0]
	v_pk_mul_f32 v[46:47], v[46:47], v[0:1] op_sel_hi:[1,0]
	v_pk_mul_f32 v[16:17], v[16:17], v[0:1] op_sel_hi:[1,0]
	v_pk_mul_f32 v[18:19], v[18:19], v[0:1] op_sel_hi:[1,0]
	v_mfma_f32_32x32x16_bf16 v[32:47], v[228:231], v[8:11], v[32:47]
	v_pk_mul_f32 v[20:21], v[20:21], v[0:1] op_sel_hi:[1,0]
	v_pk_mul_f32 v[22:23], v[22:23], v[0:1] op_sel_hi:[1,0]
	v_pk_mul_f32 v[24:25], v[24:25], v[0:1] op_sel_hi:[1,0]
	v_pk_mul_f32 v[26:27], v[26:27], v[0:1] op_sel_hi:[1,0]
	v_pk_mul_f32 v[28:29], v[28:29], v[0:1] op_sel_hi:[1,0]
	v_pk_mul_f32 v[30:31], v[30:31], v[0:1] op_sel_hi:[1,0]
	s_nop 1
	v_mfma_f32_32x32x16_bf16 v[16:31], v[198:201], v[8:11], v[16:31]
	s_waitcnt lgkmcnt(0)
	v_mfma_f32_32x32x16_bf16 v[64:79], v[232:235], v[12:15], v[64:79]
	v_mfma_f32_32x32x16_bf16 v[48:63], v[236:239], v[12:15], v[48:63]
	v_mfma_f32_32x32x16_bf16 v[32:47], v[240:243], v[12:15], v[32:47]
	v_mfma_f32_32x32x16_bf16 v[16:31], v[244:247], v[12:15], v[16:31]
	v_mov_b32_e32 v128, v215
	v_mov_b32_e32 v133, v4
	s_or_b32 s0, s24, s56
	s_and_b32 s0, s0, 0xff
	s_cmp_lg_u32 s0, 0
	s_cbranch_scc1 .LBB0_603
